# attention unit prologue: K tiles 0,1 and V tile 0 LDS-DMA issued at the top of the unit, before the Q rows are loaded and processed
# speedup vs baseline: 1.0074x; 1.0027x over previous
.LBB0_952:
	s_mov_b64 s[6:7], s[0:1]
	s_load_dwordx2 s[6:7], s[6:7], 0xa8
	s_mul_i32 s5, s24, 0x1800
	s_mov_b64 s[26:27], s[0:1]
	s_movk_i32 s19, 0x1800
	s_waitcnt lgkmcnt(0)
	s_add_u32 s5, s6, s5
	s_mul_i32 s6, s44, 0xc0
	s_addc_u32 s8, s7, 0
	s_ashr_i32 s7, s6, 31
	s_lshl_b64 s[6:7], s[6:7], 1
	s_add_u32 s6, s5, s6
	s_addc_u32 s7, s8, s7
	s_mov_b64 s[8:9], s[0:1]
	s_load_dwordx2 s[10:11], s[8:9], 0xa8
	s_mov_b64 s[8:9], s[0:1]
	s_load_dwordx2 s[8:9], s[8:9], 0xa8
	s_load_dwordx2 s[30:31], s[26:27], 0xa8
	s_mov_b64 s[26:27], s[0:1]
	s_load_dwordx2 s[26:27], s[26:27], 0xa8
	v_mbcnt_lo_u32_b32 v62, -1, 0
	v_mbcnt_hi_u32_b32 v62, -1, v62
	v_readlane_b32 s5, v254, 20
	v_ashrrev_i32_e32 v64, 4, v62
	v_lshlrev_b32_e32 v48, 3, v64
	v_ashrrev_i32_e32 v49, 31, v48
	v_and_b32_e32 v63, 15, v62
	s_waitcnt lgkmcnt(0)
	s_lshl_b32 s36, s44, 8
	s_ashr_i32 s37, s36, 31
	s_lshl_b64 s[36:37], s[36:37], 1
	s_add_u32 s48, s30, s36
	s_addc_u32 s49, s31, s37
	v_readlane_b32 s84, v254, 36
	v_ashrrev_i32_e32 v130, 5, v62
	s_nop 0
	v_add_u32_e32 v133, s84, v64
	v_xor_b32_e32 v134, v133, v62
	v_lshlrev_b32_e32 v133, 13, v133
	v_lshlrev_b32_e32 v134, 4, v134
	s_movk_i32 s86, 0xf0
	v_readlane_b32 s74, v254, 12
	v_and_or_b32 v227, v134, s86, v133
	v_bfe_u32 v131, v62, 2, 2
	v_add_u32_e32 v133, s74, v130
	v_ashrrev_i32_e32 v134, 2, v133
	v_lshrrev_b32_e32 v132, 1, v62
	v_lshlrev_b32_e32 v135, 3, v134
	v_and_or_b32 v131, v132, 8, v131
	v_and_b32_e32 v135, 0x7fff0, v135
	v_and_b32_e32 v133, 4, v133
	v_and_b32_e32 v132, 3, v62
	v_or3_b32 v133, v135, v133, v131
	v_lshlrev_b32_e32 v135, 6, v130
	v_lshlrev_b32_e32 v134, 1, v134
	v_and_b32_e32 v135, 0xc0, v135
	v_bitop3_b32 v134, v134, v132, 2 bitop3:0x6c
	v_lshl_or_b32 v134, v134, 4, v135
	v_readlane_b32 s74, v254, 37
	v_lshl_or_b32 v228, v133, 13, v134
	s_nop 0
	v_add_u32_e32 v133, s74, v64
	v_xor_b32_e32 v134, v133, v62
	v_readlane_b32 s74, v254, 38
	v_lshlrev_b32_e32 v133, 13, v133
	v_lshlrev_b32_e32 v134, 4, v134
	v_add_u32_e32 v130, s74, v130
	v_and_or_b32 v229, v134, s86, v133
	v_ashrrev_i32_e32 v133, 2, v130
	v_lshlrev_b32_e32 v134, 3, v133
	v_and_b32_e32 v135, 4, v130
	v_lshlrev_b32_e32 v130, 6, v130
	v_lshlrev_b32_e32 v133, 1, v133
	v_and_b32_e32 v134, 0x7fff0, v134
	v_and_b32_e32 v130, 0xc0, v130
	v_bitop3_b32 v132, v133, v132, 2 bitop3:0x6c
	v_ashrrev_i32_e32 v136, 3, v62
	v_or3_b32 v131, v134, v135, v131
	v_lshl_or_b32 v130, v132, 4, v130
	v_lshl_or_b32 v231, v131, 13, v130
	v_add_u32_e32 v130, s84, v136
	v_lshlrev_b32_e32 v131, 4, v62
	v_lshlrev_b32_e32 v132, 3, v130
	v_xor_b32_e32 v131, v132, v131
	v_lshlrev_b32_e32 v130, 7, v130
	s_movk_i32 s74, 0x70
	v_and_or_b32 v232, v131, s74, v130
	s_add_u32 s70, s48, 0x38000000
	s_addc_u32 s71, s49, 0
	s_add_u32 s80, s30, 0x34000000
	s_addc_u32 s81, s31, 0
	s_mov_b32 m0, s18
	s_nop 0
	global_load_lds_dwordx4 v227, s[70:71]
	s_add_i32 m0, s18, 0x400
	s_nop 0
	global_load_lds_dwordx4 v229, s[70:71]
	s_add_i32 m0, s97, 0x4000
	s_nop 0
	global_load_lds_dwordx4 v232, s[80:81]
	s_add_u32 s70, s48, 0x38080000
	s_addc_u32 s71, s49, 0
	s_add_u32 s80, s30, 0x34002000
	s_addc_u32 s81, s31, 0
	s_add_i32 m0, s18, 0x6000
	s_nop 0
	global_load_lds_dwordx4 v227, s[70:71]
	s_add_i32 m0, s18, 0x6400
	s_nop 0
	global_load_lds_dwordx4 v229, s[70:71]
	s_add_i32 m0, s97, 0xa000
	s_nop 0
	global_load_lds_dwordx4 v232, s[80:81]
	s_add_u32 s70, s48, 0x38000100
	s_addc_u32 s71, s49, 0
	s_mov_b32 m0, s95
	s_nop 0
	global_load_lds_dwordx4 v228, s[70:71]
	s_add_i32 m0, s18, 0x12400
	s_nop 0
	global_load_lds_dwordx4 v231, s[70:71]
	v_lshl_add_u64 v[0:1], v[48:49], 1, s[6:7]
	s_mov_b64 s[6:7], 0x34800000
	v_or_b32_e32 v2, s5, v63
	v_lshl_add_u64 v[0:1], v[0:1], 0, s[6:7]
	v_mad_u64_u32 v[4:5], s[6:7], v2, s19, v[0:1]
	v_or_b32_e32 v2, 16, v2
	v_mad_u64_u32 v[0:1], s[6:7], v2, s19, v[0:1]
	global_load_dwordx4 v[20:23], v[4:5], off offset:320
	global_load_dwordx4 v[40:43], v[0:1], off
	global_load_dwordx4 v[36:39], v[0:1], off offset:64
	global_load_dwordx4 v[28:31], v[0:1], off offset:128
	global_load_dwordx4 v[24:27], v[0:1], off offset:192
	global_load_dwordx4 v[32:35], v[0:1], off offset:256
	global_load_dwordx4 v[44:47], v[0:1], off offset:320
	v_or_b32_e32 v0, s4, v63
	v_add_u32_e32 v50, s5, v0
	global_load_dwordx4 v[0:3], v[4:5], off
	global_load_dwordx4 v[52:55], v[4:5], off offset:64
	global_load_dwordx4 v[12:15], v[4:5], off offset:128
	global_load_dwordx4 v[8:11], v[4:5], off offset:192
	global_load_dwordx4 v[16:19], v[4:5], off offset:256
	s_mov_b32 s4, 0x3dd53b94
	s_cmp_lg_u64 s[28:29], 0
	s_cselect_b64 s[34:35], -1, 0
	s_cmp_eq_u64 s[28:29], 0
	s_waitcnt vmcnt(0)
	v_and_b32_e32 v51, 0xffff0000, v55
	v_mul_f32_e32 v51, 0x3dd53b94, v51
	v_lshlrev_b32_e32 v6, 16, v0
	v_and_b32_e32 v0, 0xffff0000, v0
	v_mul_f32_e32 v0, 0x3dd53b94, v0
	v_mul_f32_e32 v6, 0x3dd53b94, v6
	v_cvt_pk_bf16_f32 v4, v6, v0
	v_lshlrev_b32_e32 v0, 16, v1
	v_and_b32_e32 v1, 0xffff0000, v1
	v_mul_f32_e32 v0, 0x3dd53b94, v0
	v_mul_f32_e32 v1, 0x3dd53b94, v1
	v_cvt_pk_bf16_f32 v5, v0, v1
	v_lshlrev_b32_e32 v0, 16, v2
	v_and_b32_e32 v1, 0xffff0000, v2
	v_mul_f32_e32 v0, 0x3dd53b94, v0
	v_mul_f32_e32 v1, 0x3dd53b94, v1
	v_cvt_pk_bf16_f32 v6, v0, v1
	v_lshlrev_b32_e32 v0, 16, v3
	v_and_b32_e32 v1, 0xffff0000, v3
	v_mul_f32_e32 v0, 0x3dd53b94, v0
	v_mul_f32_e32 v1, 0x3dd53b94, v1
	v_cvt_pk_bf16_f32 v7, v0, v1
	v_lshlrev_b32_e32 v0, 16, v52
	v_and_b32_e32 v1, 0xffff0000, v52
	v_mul_f32_e32 v0, 0x3dd53b94, v0
	v_mul_f32_e32 v1, 0x3dd53b94, v1
	v_cvt_pk_bf16_f32 v0, v0, v1
	v_lshlrev_b32_e32 v1, 16, v53
	v_and_b32_e32 v2, 0xffff0000, v53
	v_mul_f32_e32 v1, 0x3dd53b94, v1
	v_mul_f32_e32 v2, 0x3dd53b94, v2
	v_cvt_pk_bf16_f32 v1, v1, v2
	v_lshlrev_b32_e32 v2, 16, v54
	v_and_b32_e32 v3, 0xffff0000, v54
	v_mul_f32_e32 v2, 0x3dd53b94, v2
	v_mul_f32_e32 v3, 0x3dd53b94, v3
	v_cvt_pk_bf16_f32 v2, v2, v3
	v_lshlrev_b32_e32 v3, 16, v55
	v_mul_f32_e32 v3, 0x3dd53b94, v3
	v_cvt_pk_bf16_f32 v3, v3, v51
	v_lshlrev_b32_e32 v51, 16, v12
	v_and_b32_e32 v12, 0xffff0000, v12
	v_mul_f32_e32 v51, 0x3dd53b94, v51
	v_mul_f32_e32 v12, 0x3dd53b94, v12
	v_cvt_pk_bf16_f32 v12, v51, v12
	v_lshlrev_b32_e32 v51, 16, v13
	v_and_b32_e32 v13, 0xffff0000, v13
	v_mul_f32_e32 v51, 0x3dd53b94, v51
	v_mul_f32_e32 v13, 0x3dd53b94, v13
	v_cvt_pk_bf16_f32 v13, v51, v13
	v_lshlrev_b32_e32 v51, 16, v14
	v_and_b32_e32 v14, 0xffff0000, v14
	v_mul_f32_e32 v51, 0x3dd53b94, v51
	v_mul_f32_e32 v14, 0x3dd53b94, v14
	v_cvt_pk_bf16_f32 v14, v51, v14
	v_lshlrev_b32_e32 v51, 16, v15
	v_and_b32_e32 v15, 0xffff0000, v15
	v_mul_f32_e32 v51, 0x3dd53b94, v51
	v_mul_f32_e32 v15, 0x3dd53b94, v15
	v_cvt_pk_bf16_f32 v15, v51, v15
	v_lshlrev_b32_e32 v51, 16, v8
	v_and_b32_e32 v8, 0xffff0000, v8
	v_mul_f32_e32 v51, 0x3dd53b94, v51
	v_mul_f32_e32 v8, 0x3dd53b94, v8
	v_cvt_pk_bf16_f32 v8, v51, v8
	v_lshlrev_b32_e32 v51, 16, v9
	v_and_b32_e32 v9, 0xffff0000, v9
	v_mul_f32_e32 v51, 0x3dd53b94, v51
	v_mul_f32_e32 v9, 0x3dd53b94, v9
	v_cvt_pk_bf16_f32 v9, v51, v9
	v_lshlrev_b32_e32 v51, 16, v10
	v_and_b32_e32 v10, 0xffff0000, v10
	v_mul_f32_e32 v51, 0x3dd53b94, v51
	v_mul_f32_e32 v10, 0x3dd53b94, v10
	v_cvt_pk_bf16_f32 v10, v51, v10
	v_lshlrev_b32_e32 v51, 16, v11
	v_and_b32_e32 v11, 0xffff0000, v11
	v_mul_f32_e32 v51, 0x3dd53b94, v51
	v_mul_f32_e32 v11, 0x3dd53b94, v11
	v_cvt_pk_bf16_f32 v11, v51, v11
	v_ashrrev_i32_e32 v51, 31, v50
	v_lshlrev_b64 v[52:53], 8, v[50:51]
	v_lshlrev_b32_e32 v55, 16, v16
	v_lshlrev_b32_e32 v54, 16, v17
	v_and_b32_e32 v57, 0xffff0000, v16
	v_and_b32_e32 v56, 0xffff0000, v17
	v_lshl_add_u64 v[52:53], s[28:29], 0, v[52:53]
	v_pk_mul_f32 v[60:61], v[54:55], s[4:5] op_sel_hi:[1,0]
	v_pk_mul_f32 v[54:55], v[56:57], s[4:5] op_sel_hi:[1,0]
	v_lshlrev_b32_e32 v17, 16, v18
	v_lshlrev_b32_e32 v16, 16, v19
	v_and_b32_e32 v57, 0xffff0000, v18
	v_and_b32_e32 v56, 0xffff0000, v19
	v_pk_mul_f32 v[58:59], v[16:17], s[4:5] op_sel_hi:[1,0]
	v_pk_mul_f32 v[56:57], v[56:57], s[4:5] op_sel_hi:[1,0]
	v_lshl_add_u64 v[52:53], v[48:49], 2, v[52:53]
	s_cbranch_scc1 .LBB0_954
	global_load_dwordx4 v[16:19], v[52:53], off offset:16
	global_load_dwordx4 v[66:69], v[52:53], off
	v_add_co_u32_e32 v124, vcc, 0x1000, v52
	global_load_dwordx4 v[100:103], v[52:53], off offset:144
	global_load_dwordx4 v[104:107], v[52:53], off offset:128
	v_addc_co_u32_e32 v125, vcc, 0, v53, vcc
	global_load_dwordx4 v[108:111], v[124:125], off offset:16
	global_load_dwordx4 v[112:115], v[124:125], off
	global_load_dwordx4 v[116:119], v[124:125], off offset:144
	global_load_dwordx4 v[120:123], v[124:125], off offset:128
	s_waitcnt vmcnt(6)
	v_mov_b32_e32 v71, v66
	v_mov_b32_e32 v66, v69
	v_mov_b32_e32 v70, v68
	v_pk_mul_f32 v[68:69], v[54:55], v[66:67]
	s_nop 0
	v_pk_fma_f32 v[68:69], v[60:61], v[70:71], v[68:69] neg_lo:[0,0,1] neg_hi:[0,0,1]
	v_pk_mul_f32 v[60:61], v[60:61], v[66:67]
	s_nop 0
	v_pk_fma_f32 v[54:55], v[54:55], v[70:71], v[60:61]
	v_mov_b32_e32 v61, v16
	v_mov_b32_e32 v16, v19
	v_mov_b32_e32 v60, v18
	v_pk_mul_f32 v[18:19], v[56:57], v[16:17]
	v_pk_mul_f32 v[16:17], v[58:59], v[16:17]
	v_pk_fma_f32 v[18:19], v[58:59], v[60:61], v[18:19] neg_lo:[0,0,1] neg_hi:[0,0,1]
	v_pk_fma_f32 v[56:57], v[56:57], v[60:61], v[16:17]
	v_mov_b64_e32 v[58:59], v[18:19]
	v_mov_b64_e32 v[60:61], v[68:69]

.Lmy_prio_skip:
	s_add_i32 s34, s97, 0
	s_add_i32 m0, s18, 0x400
	v_lshlrev_b32_e32 v60, 8, v63
	s_add_i32 m0, s34, 0x4000
	v_and_b32_e32 v61, -16, v62
	s_add_u32 s8, s19, 0x38080000
	s_addc_u32 s9, s25, 0
	s_add_u32 s10, s30, 0x34002000
	s_addc_u32 s11, s31, 0
	s_add_i32 m0, s18, 0x6000
	v_lshlrev_b32_e32 v92, 4, v63
	s_add_i32 m0, s18, 0x6400
	v_xad_u32 v225, v92, v61, v60
	s_add_i32 m0, s34, 0xa000
	s_mov_b64 s[8:9], s[28:29]
	s_mov_b32 m0, s95
	v_add_u32_e32 v72, 0, v225
	s_add_i32 m0, s18, 0x12400
	v_add_u32_e32 v93, 64, v61
	s_add_u32 s8, s19, 0x38100000
	s_addc_u32 s9, s25, 0
	s_add_u32 s10, s30, 0x34004000
	s_waitcnt vmcnt(5)
	s_addc_u32 s11, s31, 0
	s_add_i32 m0, s18, 0xc000
	s_barrier
	v_xad_u32 v234, v93, v92, v60
	global_load_lds_dwordx4 v227, s[8:9]
	s_add_i32 m0, s18, 0xc400
	v_add_u32_e32 v94, 0, v234
	global_load_lds_dwordx4 v229, s[8:9]
	s_add_i32 m0, s34, 0x10000
	s_add_u32 s4, s4, 0x38080100
	global_load_lds_dwordx4 v232, s[10:11]
	s_addc_u32 s5, s5, 0
	s_add_i32 m0, s18, 0x16000
	v_lshlrev_b32_e32 v97, 3, v62
	global_load_lds_dwordx4 v228, s[4:5]
	s_add_i32 m0, s18, 0x16400
	s_mov_b32 s8, 0x3fffffc
	global_load_lds_dwordx4 v231, s[4:5]
	ds_read_b128 v[48:51], v72
	ds_read_b128 v[52:55], v72 offset:4096
	ds_read_b128 v[68:71], v72 offset:8192
	ds_read_b128 v[72:75], v72 offset:12288
	ds_read_b128 v[84:87], v94
	ds_read_b128 v[88:91], v94 offset:4096
	s_waitcnt lgkmcnt(0)
	v_mfma_f32_16x16x32_bf16 v[56:59], v[48:51], v[4:7], 0
	v_mov_b32_e32 v204, 1.0
	v_mov_b32_e32 v200, 0
	s_mov_b32 s25, 1
	v_mfma_f32_16x16x32_bf16 v[48:51], v[48:51], v[40:43], 0
	s_mov_b32 s4, 4
	s_mov_b32 s5, 2
	v_mov_b32_e32 v201, v200
	v_mfma_f32_16x16x32_bf16 v[64:67], v[52:55], v[4:7], 0
	v_mov_b32_e32 v205, v204
	v_mfma_f32_16x16x32_bf16 v[52:55], v[52:55], v[40:43], 0
	v_mfma_f32_16x16x32_bf16 v[76:79], v[68:71], v[4:7], 0
	v_mfma_f32_16x16x32_bf16 v[68:71], v[68:71], v[40:43], 0
	v_mfma_f32_16x16x32_bf16 v[56:59], v[84:87], v[0:3], v[56:59]
	v_mfma_f32_16x16x32_bf16 v[48:51], v[84:87], v[36:39], v[48:51]
	v_mfma_f32_16x16x32_bf16 v[64:67], v[88:91], v[0:3], v[64:67]
	v_mfma_f32_16x16x32_bf16 v[52:55], v[88:91], v[36:39], v[52:55]
	ds_read_b128 v[84:87], v94 offset:8192
	ds_read_b128 v[88:91], v94 offset:12288
	v_mfma_f32_16x16x32_bf16 v[80:83], v[72:75], v[4:7], 0
	v_mfma_f32_16x16x32_bf16 v[72:75], v[72:75], v[40:43], 0
	s_waitcnt lgkmcnt(0)
	v_mfma_f32_16x16x32_bf16 v[76:79], v[84:87], v[0:3], v[76:79]
	v_mfma_f32_16x16x32_bf16 v[68:71], v[84:87], v[36:39], v[68:71]
	v_add_u32_e32 v84, 0x80, v61
	v_xad_u32 v233, v84, v92, v60
	v_add_u32_e32 v94, 0, v233
	v_mfma_f32_16x16x32_bf16 v[80:83], v[88:91], v[0:3], v[80:83]
	v_mfma_f32_16x16x32_bf16 v[72:75], v[88:91], v[36:39], v[72:75]
	ds_read_b128 v[84:87], v94
	ds_read_b128 v[88:91], v94 offset:4096
	s_waitcnt lgkmcnt(0)
	v_mfma_f32_16x16x32_bf16 v[56:59], v[84:87], v[12:15], v[56:59]
	v_mfma_f32_16x16x32_bf16 v[48:51], v[84:87], v[28:31], v[48:51]
	v_mfma_f32_16x16x32_bf16 v[64:67], v[88:91], v[12:15], v[64:67]
	v_mfma_f32_16x16x32_bf16 v[52:55], v[88:91], v[28:31], v[52:55]
	ds_read_b128 v[84:87], v94 offset:8192
	ds_read_b128 v[88:91], v94 offset:12288
	s_waitcnt lgkmcnt(0)
	v_mfma_f32_16x16x32_bf16 v[76:79], v[84:87], v[12:15], v[76:79]
	v_mfma_f32_16x16x32_bf16 v[68:71], v[84:87], v[28:31], v[68:71]
	v_add_u32_e32 v84, 0xc0, v61
	v_xad_u32 v230, v84, v92, v60
	v_add_u32_e32 v60, 0, v230
	v_mfma_f32_16x16x32_bf16 v[80:83], v[88:91], v[12:15], v[80:83]
	v_and_b32_e32 v92, 0x70, v97
	v_mfma_f32_16x16x32_bf16 v[72:75], v[88:91], v[28:31], v[72:75]
	ds_read_b128 v[84:87], v60
	ds_read_b128 v[88:91], v60 offset:4096
	s_waitcnt lgkmcnt(0)
	v_mfma_f32_16x16x32_bf16 v[56:59], v[84:87], v[8:11], v[56:59]
	v_mfma_f32_16x16x32_bf16 v[48:51], v[84:87], v[24:27], v[48:51]
	v_mfma_f32_16x16x32_bf16 v[64:67], v[88:91], v[8:11], v[64:67]
	v_mfma_f32_16x16x32_bf16 v[52:55], v[88:91], v[24:27], v[52:55]
	ds_read_b128 v[84:87], v60 offset:8192
	ds_read_b128 v[88:91], v60 offset:12288
	v_lshlrev_b32_e32 v60, 7, v63
	v_xad_u32 v226, v92, v61, v60
	v_add_u32_e32 v61, 0, v226
	s_waitcnt lgkmcnt(0)
	v_mfma_f32_16x16x32_bf16 v[76:79], v[84:87], v[8:11], v[76:79]
	v_xad_u32 v224, v93, v92, v60
	v_add_u32_e32 v60, 0, v224
	v_mfma_f32_16x16x32_bf16 v[68:71], v[84:87], v[24:27], v[68:71]
	v_mfma_f32_16x16x32_bf16 v[80:83], v[88:91], v[8:11], v[80:83]
	v_mfma_f32_16x16x32_bf16 v[72:75], v[88:91], v[24:27], v[72:75]
	ds_read_b128 v[84:87], v61 offset:16384
	ds_read_b128 v[88:91], v61 offset:18432
	s_waitcnt lgkmcnt(0)
	v_mfma_f32_16x16x32_bf16 v[56:59], v[84:87], v[16:19], v[56:59]
	v_mfma_f32_16x16x32_bf16 v[48:51], v[84:87], v[32:35], v[48:51]
	v_mfma_f32_16x16x32_bf16 v[64:67], v[88:91], v[16:19], v[64:67]
	v_mfma_f32_16x16x32_bf16 v[52:55], v[88:91], v[32:35], v[52:55]
	ds_read_b128 v[84:87], v61 offset:20480
	ds_read_b128 v[88:91], v61 offset:22528
	v_lshrrev_b32_e32 v61, 2, v63
	v_and_or_b32 v61, v96, s8, v61
	s_waitcnt lgkmcnt(0)
	v_mfma_f32_16x16x32_bf16 v[76:79], v[84:87], v[16:19], v[76:79]
	s_mov_b32 s8, 0
	s_mov_b32 s10, s8
	s_mov_b32 s11, s8
	v_mfma_f32_16x16x32_bf16 v[68:71], v[84:87], v[32:35], v[68:71]
	s_mov_b32 s9, s8
	v_mfma_f32_16x16x32_bf16 v[80:83], v[88:91], v[16:19], v[80:83]
	v_mfma_f32_16x16x32_bf16 v[72:75], v[88:91], v[32:35], v[72:75]
	ds_read_b128 v[84:87], v60 offset:16384
	ds_read_b128 v[88:91], v60 offset:18432
	s_waitcnt lgkmcnt(0)
	v_mfma_f32_16x16x32_bf16 v[56:59], v[84:87], v[20:23], v[56:59]
	v_mfma_f32_16x16x32_bf16 v[84:87], v[84:87], v[44:47], v[48:51]
	s_nop 2
	ds_read_b128 v[48:51], v60 offset:20480
	v_mfma_f32_16x16x32_bf16 v[92:95], v[88:91], v[44:47], v[52:55]
	s_nop 2
	ds_read_b128 v[52:55], v60 offset:22528
	v_bfe_u32 v60, v62, 4, 1
	v_lshlrev_b32_e32 v63, 11, v60
	s_waitcnt lgkmcnt(0)
	v_mfma_f32_16x16x32_bf16 v[76:79], v[48:51], v[20:23], v[76:79]
	v_mfma_f32_16x16x32_bf16 v[68:71], v[48:51], v[44:47], v[68:71]
	v_lshl_add_u32 v48, v61, 6, v63
	v_and_or_b32 v48, v97, 24, v48
	v_lshlrev_b32_e32 v49, 5, v60
	v_mfma_f32_16x16x32_bf16 v[64:67], v[88:91], v[20:23], v[64:67]
	v_or_b32_e32 v223, v48, v49
	v_bitop3_b32 v222, v48, 32, v49 bitop3:0x36
	v_max_f32_e32 v48, v85, v85
	v_max_f32_e32 v49, v84, v84
	v_max_f32_e32 v48, v49, v48
	v_max_f32_e32 v49, v57, v57
	v_max_f32_e32 v50, v56, v56
	v_max_f32_e32 v49, v50, v49
	v_max3_f32 v48, v48, v86, v87
	v_max3_f32 v49, v49, v58, v59
	v_mfma_f32_16x16x32_bf16 v[80:83], v[52:55], v[20:23], v[80:83]
	v_max3_f32 v48, v48, v92, v93
	v_max3_f32 v49, v49, v64, v65
	v_max3_f32 v48, v48, v94, v95
	v_mfma_f32_16x16x32_bf16 v[72:75], v[52:55], v[44:47], v[72:75]
	v_max3_f32 v49, v49, v66, v67
	v_max3_f32 v48, v48, v68, v69
	v_max3_f32 v49, v49, v76, v77
	v_max3_f32 v48, v48, v70, v71
	v_max3_f32 v49, v49, v78, v79
	s_nop 2
	v_max3_f32 v48, v48, v72, v73
	v_max3_f32 v49, v49, v80, v81
	v_lshlrev_b32_e32 v50, 2, v62
	v_max3_f32 v48, v48, v74, v75
	v_max3_f32 v49, v49, v82, v83
	v_xor_b32_e32 v220, 64, v50
	ds_bpermute_b32 v51, v220, v49
	ds_bpermute_b32 v52, v220, v48
	v_xor_b32_e32 v221, 0x80, v50
	v_mov_b64_e32 v[90:91], s[10:11]
	v_mov_b64_e32 v[88:89], s[8:9]
	s_waitcnt lgkmcnt(0)
	v_max_f32_e32 v50, v51, v51
	v_max_f32_e32 v51, v52, v52
	v_max_f32_e32 v48, v48, v51
	ds_bpermute_b32 v51, v221, v48
	v_max_f32_e32 v49, v49, v50
	ds_bpermute_b32 v50, v221, v49
	s_add_u32 s10, s30, 0x34008000
	v_mov_b64_e32 v[102:103], v[90:91]
	s_waitcnt lgkmcnt(0)
	v_max_f32_e32 v51, v51, v51
	v_max_f32_e32 v51, v48, v51
	v_max_f32_e32 v48, v50, v50
	v_max_f32_e32 v50, v49, v48
	v_pk_add_f32 v[202:203], v[50:51], 0 op_sel_hi:[1,0]
	v_sub_f32_e32 v53, v94, v51
	v_pk_add_f32 v[48:49], v[202:203], 0 neg_lo:[1,1] neg_hi:[1,1]
	v_sub_f32_e32 v54, v93, v51
	v_sub_f32_e32 v49, v95, v51
	v_exp_f32_e32 v137, v54
	v_exp_f32_e32 v138, v53
	v_exp_f32_e32 v139, v49
	v_sub_f32_e32 v49, v67, v50
	v_sub_f32_e32 v53, v66, v50
	v_sub_f32_e32 v54, v65, v50
	v_sub_f32_e32 v131, v75, v51
	v_sub_f32_e32 v130, v74, v51
	v_sub_f32_e32 v129, v73, v51
	v_sub_f32_e32 v128, v72, v51
	v_sub_f32_e32 v143, v71, v51
	v_sub_f32_e32 v142, v70, v51
	v_sub_f32_e32 v141, v69, v51
	v_sub_f32_e32 v140, v68, v51
	v_sub_f32_e32 v55, v92, v51
	v_exp_f32_e32 v153, v54
	v_exp_f32_e32 v154, v53
	v_exp_f32_e32 v155, v49
	v_sub_f32_e32 v49, v87, v51
	v_sub_f32_e32 v53, v86, v51
	v_sub_f32_e32 v54, v85, v51
	v_sub_f32_e32 v51, v84, v51
	v_sub_f32_e32 v135, v83, v50
	v_sub_f32_e32 v134, v82, v50
	v_sub_f32_e32 v133, v81, v50
	v_sub_f32_e32 v132, v80, v50
	v_sub_f32_e32 v151, v79, v50
	v_sub_f32_e32 v150, v78, v50
	v_sub_f32_e32 v149, v77, v50
	v_sub_f32_e32 v148, v76, v50
	v_exp_f32_e32 v136, v55
	v_sub_f32_e32 v55, v64, v50
	v_exp_f32_e32 v144, v51
	v_exp_f32_e32 v146, v53
	v_exp_f32_e32 v147, v49
	v_sub_f32_e32 v49, v59, v50
	v_sub_f32_e32 v51, v58, v50
	v_sub_f32_e32 v53, v57, v50
	v_sub_f32_e32 v50, v56, v50
	v_exp_f32_e32 v152, v55
	v_exp_f32_e32 v145, v54
	v_exp_f32_e32 v156, v50
	v_exp_f32_e32 v157, v53
	v_exp_f32_e32 v158, v51
	v_exp_f32_e32 v159, v49
	v_xor_b32_e32 v52, 0x80000000, v203
	v_mov_b64_e32 v[106:107], v[90:91]
	v_mov_b64_e32 v[118:119], v[90:91]
	v_mov_b64_e32 v[56:57], v[88:89]
	v_mov_b64_e32 v[64:65], v[88:89]
	v_mov_b64_e32 v[72:73], v[88:89]
	v_mov_b64_e32 v[80:81], v[88:89]
	v_mov_b64_e32 v[94:95], v[90:91]
	v_mov_b64_e32 v[98:99], v[90:91]
	v_mov_b64_e32 v[110:111], v[90:91]
	v_mov_b64_e32 v[114:115], v[90:91]
	v_mov_b64_e32 v[84:85], v[88:89]
	v_mov_b64_e32 v[76:77], v[88:89]
	v_mov_b64_e32 v[68:69], v[88:89]
	v_mov_b64_e32 v[60:61], v[88:89]
	s_addc_u32 s11, s31, 0
	s_mov_b64 s[30:31], 0
	v_mov_b64_e32 v[100:101], v[88:89]
	v_mov_b64_e32 v[104:105], v[88:89]
	v_mov_b64_e32 v[116:117], v[88:89]
	v_mov_b64_e32 v[58:59], v[90:91]
	v_mov_b64_e32 v[66:67], v[90:91]
	v_mov_b64_e32 v[74:75], v[90:91]
	v_mov_b64_e32 v[82:83], v[90:91]
	v_mov_b64_e32 v[92:93], v[88:89]
	v_mov_b64_e32 v[96:97], v[88:89]
	v_mov_b64_e32 v[108:109], v[88:89]
	v_mov_b64_e32 v[112:113], v[88:89]
	v_mov_b64_e32 v[86:87], v[90:91]
	v_mov_b64_e32 v[78:79], v[90:91]
	v_mov_b64_e32 v[70:71], v[90:91]
	v_mov_b64_e32 v[62:63], v[90:91]
	v_mov_b32_e32 v53, v52
	v_mov_b32_e32 v54, v52
	v_mov_b32_e32 v55, v52
	v_mov_b32_e32 v49, v48
	v_mov_b32_e32 v50, v48
	v_mov_b32_e32 v51, v48
